# attention fast path: drop to s_setprio 0 at the start of the interleaved QK/exp section (plus pk adds)
# speedup vs baseline: 1.0026x; 1.0026x over previous
; #define LAS __attribute__((address_space(3)))
; #define MFMA32(a, b, c) __builtin_amdgcn_mfma_f32_32x32x16_bf16((a), (b), (c), 0, 0, 0)
; DI int crow(int r, int hi) { return (r & 3) + 8 * (r >> 2) + 4 * hi; }
; DI void attn_tile(bool MASK, const LAS unsigned char* Ks, const LAS unsigned char* Vs, const bf16x8 (&qr)[6], f32x16& negm, float& mrun, float& lrun, f32x16& o0, f32x16& o1,
;                                        int kv0, int qrow, int r32, int hi) {
;     ...
;     __builtin_amdgcn_s_setprio(1);
;     {
;         const bf16x8 a0 = *(const LAS bf16x8*)(Ks + r32 * 208 + hi * 16);
;         const bf16x8 a1 = *(const LAS bf16x8*)(Ks + (32 + r32) * 208 + hi * 16);
;         p0 = MFMA32(a0, qr[0], negm); p1 = MFMA32(a1, qr[0], negm);
;     }
; #pragma unroll
;     for (int d0 = 1; d0 < 6; ++d0) {
;         const bf16x8 a0 = *(const LAS bf16x8*)(Ks + r32 * 208 + (2 * d0 + hi) * 16);
;         const bf16x8 a1 = *(const LAS bf16x8*)(Ks + (32 + r32) * 208 + (2 * d0 + hi) * 16);
;         p0 = MFMA32(a0, qr[d0], p0); p1 = MFMA32(a1, qr[d0], p1);
;     }
;     __builtin_amdgcn_s_setprio(0);
;     if (MASK) {
;         asm volatile("" ::: "memory");
; #pragma unroll
;         for (int r = 0; r < 16; ++r) { const int kv = kv0 + crow(r, hi); if (kv > qrow) p0[r] = -INFINITY; if (kv + 32 > qrow) p1[r] = -INFINITY; }
;     }
;     float mxa = max3f(p0[0], p0[1], p1[0]), mxb = max3f(p0[2], p0[3], p1[1]); mxa = max3f(mxa, p1[2], p1[3]);
; #pragma unroll
;     for (int r = 4; r < 16; r += 4) { mxa = max3f(mxa, p0[r], p0[r + 1]); mxb = max3f(mxb, p0[r + 2], p0[r + 3]); mxa = max3f(mxa, p1[r], p1[r + 1]); mxb = max3f(mxb, p1[r + 2], p1[r + 3]); }
;     float mx = max2f(mxa, mxb);
;     mx = max2f(mx, __shfl_xor(mx, 32));
;     if (__any(mx > AT_THR)) {
;         const float dm = max2f(mx, 0.f);
;         const float alpha = __builtin_amdgcn_exp2f(-dm);
;         mrun += dm; lrun *= alpha;
; #pragma unroll
;         for (int r = 0; r < 16; ++r) { o0[r] *= alpha; o1[r] *= alpha; p0[r] -= dm; p1[r] -= dm; negm[r] = -mrun; }
;     }
; DI void attn_unit(int b, int h, int qb, const bf16* Qb, const bf16* Kb, const bf16* Vt, const int* positions, bf16* O, LAS unsigned char* lds, int tid) {
;     ...
;     for (int t = 0; t < NT; t += 3) {
;         __syncthreads();
;         AT_COMMIT(B, 1); AT_ISSUE(B, t + 4);
;         AT_TILE(t, 0);
.LBB0_849:
	s_add_i32 s33, s23, 4
	s_min_i32 s33, s33, s20
	v_mad_i64_i32 v[4:5], s[34:35], s33, v161, v[190:191]
	v_mad_i64_i32 v[6:7], s[34:35], s33, v161, v[194:195]
	v_add3_u32 v0, v204, v199, s29
	s_lshl_b32 s34, s33, 6
	s_waitcnt lgkmcnt(0)
	s_barrier
	s_waitcnt vmcnt(3)
	ds_write_b128 v209, v[130:133] offset:22016
	ds_write_b128 v210, v[106:109] offset:22016
	ds_write2_b64 v0, v[110:111], v[112:113] offset1:1
	s_ashr_i32 s35, s34, 31
	global_load_dwordx4 v[130:133], v[4:5], off
	global_load_dwordx4 v[106:109], v[6:7], off
	v_lshl_add_u64 v[4:5], s[34:35], 1, v[192:193]
	global_load_dwordx4 v[110:113], v[4:5], off
	s_cmp_gt_i32 s21, s22
	s_cbranch_scc1 .LBB0_855
	s_cmp_lt_i32 s23, s12
	s_setprio 1
	v_add_u32_e32 v0, v206, v160
	ds_read_b128 v[4:7], v0
	ds_read_b128 v[8:11], v0 offset:32
	ds_read_b128 v[12:15], v0 offset:64
	ds_read_b128 v[214:217], v0 offset:96
	ds_read_b128 v[218:221], v0 offset:128
	ds_read_b128 v[222:225], v0 offset:160
	ds_read_b128 v[226:229], v0 offset:6656
	ds_read_b128 v[230:233], v0 offset:6688
	s_waitcnt lgkmcnt(7)
	v_mfma_f32_32x32x16_bf16 v[82:97], v[4:7], v[154:157], v[50:65]
	ds_read_b128 v[234:237], v0 offset:6720
	s_waitcnt lgkmcnt(7)
	v_mfma_f32_32x32x16_bf16 v[82:97], v[8:11], v[150:153], v[82:97]
	ds_read_b128 v[238:241], v0 offset:6752
	s_waitcnt lgkmcnt(7)
	v_mfma_f32_32x32x16_bf16 v[82:97], v[12:15], v[146:149], v[82:97]
	ds_read_b128 v[242:245], v0 offset:6784
	s_waitcnt lgkmcnt(7)
	v_mfma_f32_32x32x16_bf16 v[82:97], v[214:217], v[126:129], v[82:97]
	ds_read_b128 v[246:249], v0 offset:6816
	s_waitcnt lgkmcnt(7)
	v_mfma_f32_32x32x16_bf16 v[82:97], v[218:221], v[122:125], v[82:97]
	s_waitcnt lgkmcnt(6)
	v_mfma_f32_32x32x16_bf16 v[82:97], v[222:225], v[118:121], v[82:97]
	s_cbranch_scc0 .Lat_m0
	s_setprio 0
	v_add_u32_e32 v3, v205, v208
	v_add_u32_e32 v0, 0x4000, v3
	v_add_u32_e32 v3, 0x3000, v3
	s_waitcnt lgkmcnt(5)
	v_mfma_f32_32x32x16_bf16 v[66:81], v[226:229], v[154:157], v[50:65]
	ds_read2_b64 v[226:229], v3 offset0:128 offset1:130
	s_waitcnt lgkmcnt(5)
	v_mfma_f32_32x32x16_bf16 v[66:81], v[230:233], v[150:153], v[66:81]
	ds_read2_b64 v[230:233], v0 offset0:160 offset1:162
	s_nop 3
	v_exp_f32_e32 v214, v82
	v_exp_f32_e32 v215, v83
	v_exp_f32_e32 v216, v84
	s_waitcnt lgkmcnt(5)
	v_mfma_f32_32x32x16_bf16 v[66:81], v[234:237], v[146:149], v[66:81]
	ds_read2_b64 v[234:237], v3 offset0:132 offset1:134
	v_exp_f32_e32 v217, v85
	v_exp_f32_e32 v218, v86
	v_exp_f32_e32 v219, v87
	s_waitcnt lgkmcnt(5)
	v_mfma_f32_32x32x16_bf16 v[66:81], v[238:241], v[126:129], v[66:81]
	ds_read2_b64 v[238:241], v0 offset0:164 offset1:166
	v_exp_f32_e32 v220, v88
	v_exp_f32_e32 v221, v89
	v_max3_f32 v159, v82, v83, v84
	v_max3_f32 v250, v85, v86, v87
	s_waitcnt lgkmcnt(5)
	v_mfma_f32_32x32x16_bf16 v[66:81], v[242:245], v[122:125], v[66:81]
	ds_read2_b64 v[242:245], v3 offset0:136 offset1:138
	v_exp_f32_e32 v222, v90
	v_exp_f32_e32 v223, v91
	v_exp_f32_e32 v224, v92
	s_waitcnt lgkmcnt(5)
	v_mfma_f32_32x32x16_bf16 v[66:81], v[246:249], v[118:121], v[66:81]
	ds_read2_b64 v[246:249], v0 offset0:168 offset1:170
	s_setprio 0
	v_exp_f32_e32 v225, v93
	v_exp_f32_e32 v12, v94
	v_exp_f32_e32 v13, v95
	v_exp_f32_e32 v14, v96
	v_exp_f32_e32 v15, v97
	v_max3_f32 v159, v159, v88, v89
	v_max3_f32 v250, v250, v90, v91
	v_max3_f32 v159, v159, v92, v93
	v_max3_f32 v250, v250, v94, v95
	v_max3_f32 v159, v159, v96, v97
	s_nop 1
	v_max3_f32 v159, v159, v66, v67
	v_max3_f32 v250, v250, v68, v69
	v_max3_f32 v159, v159, v70, v71
	v_max3_f32 v250, v250, v72, v73
	v_max3_f32 v159, v159, v74, v75
	v_max3_f32 v250, v250, v76, v77
	v_max3_f32 v159, v159, v78, v79
	v_max3_f32 v250, v250, v80, v81
	v_max_f32_e32 v0, v159, v250
	v_mov_b32_e32 v3, v0
	s_nop 1
	v_permlane32_swap_b32_e32 v0, v3
	v_max_f32_e32 v0, v0, v3
	s_nop 0
	v_cmp_lt_f32_e32 vcc, s30, v0
	s_cbranch_vccnz .Lat_r0

; #define LAS __attribute__((address_space(3)))
; #define MFMA32(a, b, c) __builtin_amdgcn_mfma_f32_32x32x16_bf16((a), (b), (c), 0, 0, 0)
; DI int crow(int r, int hi) { return (r & 3) + 8 * (r >> 2) + 4 * hi; }
; DI float max2f(float a, float b) { float r; asm("v_max_f32_e32 %0, %1, %2" : "=v"(r) : "v"(a), "v"(b)); return r; }
; DI void attn_tile(bool MASK, const LAS unsigned char* Ks, const LAS unsigned char* Vs, const bf16x8 (&qr)[6], f32x16& negm, float& mrun, float& lrun, f32x16& o0, f32x16& o1,
;                                        int kv0, int qrow, int r32, int hi) {
;     ...
;     __builtin_amdgcn_s_setprio(1);
;     {
;         const bf16x8 a0 = *(const LAS bf16x8*)(Ks + r32 * 208 + hi * 16);
;         const bf16x8 a1 = *(const LAS bf16x8*)(Ks + (32 + r32) * 208 + hi * 16);
;         p0 = MFMA32(a0, qr[0], negm); p1 = MFMA32(a1, qr[0], negm);
;     }
; #pragma unroll
;     for (int d0 = 1; d0 < 6; ++d0) {
;         const bf16x8 a0 = *(const LAS bf16x8*)(Ks + r32 * 208 + (2 * d0 + hi) * 16);
;         const bf16x8 a1 = *(const LAS bf16x8*)(Ks + (32 + r32) * 208 + (2 * d0 + hi) * 16);
;         p0 = MFMA32(a0, qr[d0], p0); p1 = MFMA32(a1, qr[d0], p1);
;     }
;     __builtin_amdgcn_s_setprio(0);
;     if (MASK) {
;         asm volatile("" ::: "memory");
; #pragma unroll
;         for (int r = 0; r < 16; ++r) { const int kv = kv0 + crow(r, hi); if (kv > qrow) p0[r] = -INFINITY; if (kv + 32 > qrow) p1[r] = -INFINITY; }
;     }
;     float mxa = max3f(p0[0], p0[1], p1[0]), mxb = max3f(p0[2], p0[3], p1[1]); mxa = max3f(mxa, p1[2], p1[3]);
; #pragma unroll
;     for (int r = 4; r < 16; r += 4) { mxa = max3f(mxa, p0[r], p0[r + 1]); mxb = max3f(mxb, p0[r + 2], p0[r + 3]); mxa = max3f(mxa, p1[r], p1[r + 1]); mxb = max3f(mxb, p1[r + 2], p1[r + 3]); }
;     float mx = max2f(mxa, mxb);
;     mx = max2f(mx, __shfl_xor(mx, 32));
;     if (__any(mx > AT_THR)) {
;         const float dm = max2f(mx, 0.f);
;         const float alpha = __builtin_amdgcn_exp2f(-dm);
;         mrun += dm; lrun *= alpha;
; #pragma unroll
;         for (int r = 0; r < 16; ++r) { o0[r] *= alpha; o1[r] *= alpha; p0[r] -= dm; p1[r] -= dm; negm[r] = -mrun; }
;     }
; DI void attn_unit(int b, int h, int qb, const bf16* Qb, const bf16* Kb, const bf16* Vt, const int* positions, bf16* O, LAS unsigned char* lds, int tid) {
;     ...
;         AT_COMMIT(C, 2); AT_ISSUE(C, t + 5);
;         AT_TILE(t + 1, 1);
.LBB0_855:
	s_add_i32 s33, s23, 5
	s_min_i32 s33, s33, s20
	v_mad_i64_i32 v[4:5], s[34:35], s33, v161, v[190:191]
	v_mad_i64_i32 v[6:7], s[34:35], s33, v161, v[194:195]
	v_add3_u32 v0, v204, v199, s31
	s_lshl_b32 s34, s33, 6
	s_waitcnt lgkmcnt(0)
	s_barrier
	ds_write_b128 v209, v[98:101] offset:44032
	ds_write_b128 v210, v[102:105] offset:44032
	ds_write2_b64 v0, v[114:115], v[116:117] offset1:1
	s_ashr_i32 s35, s34, 31
	global_load_dwordx4 v[98:101], v[4:5], off
	global_load_dwordx4 v[102:105], v[6:7], off
	v_lshl_add_u64 v[4:5], s[34:35], 1, v[192:193]
	global_load_dwordx4 v[114:117], v[4:5], off
	s_add_i32 s33, s23, 1
	s_cmp_ge_i32 s33, s19
	s_cbranch_scc1 .LBB0_862
	s_add_i32 s34, s21, 64
	s_cmp_gt_i32 s34, s22
	s_cbranch_scc1 .LBB0_862
	s_cmp_lt_i32 s33, s12
	s_setprio 1
	v_add_u32_e32 v0, v206, v160
	ds_read_b128 v[4:7], v0 offset:22016
	ds_read_b128 v[8:11], v0 offset:22048
	ds_read_b128 v[12:15], v0 offset:22080
	ds_read_b128 v[214:217], v0 offset:22112
	ds_read_b128 v[218:221], v0 offset:22144
	ds_read_b128 v[222:225], v0 offset:22176
	ds_read_b128 v[226:229], v0 offset:28672
	ds_read_b128 v[230:233], v0 offset:28704
	s_waitcnt lgkmcnt(7)
	v_mfma_f32_32x32x16_bf16 v[82:97], v[4:7], v[154:157], v[50:65]
	ds_read_b128 v[234:237], v0 offset:28736
	s_waitcnt lgkmcnt(7)
	v_mfma_f32_32x32x16_bf16 v[82:97], v[8:11], v[150:153], v[82:97]
	ds_read_b128 v[238:241], v0 offset:28768
	s_waitcnt lgkmcnt(7)
	v_mfma_f32_32x32x16_bf16 v[82:97], v[12:15], v[146:149], v[82:97]
	ds_read_b128 v[242:245], v0 offset:28800
	s_waitcnt lgkmcnt(7)
	v_mfma_f32_32x32x16_bf16 v[82:97], v[214:217], v[126:129], v[82:97]
	ds_read_b128 v[246:249], v0 offset:28832
	s_waitcnt lgkmcnt(7)
	v_mfma_f32_32x32x16_bf16 v[82:97], v[218:221], v[122:125], v[82:97]
	s_waitcnt lgkmcnt(6)
	v_mfma_f32_32x32x16_bf16 v[82:97], v[222:225], v[118:121], v[82:97]
	s_cbranch_scc0 .Lat_m1
	s_setprio 0
	v_add_u32_e32 v3, v205, v208
	v_add_u32_e32 v0, 0x9800, v3
	v_add_u32_e32 v3, 0x8800, v3
	s_waitcnt lgkmcnt(5)
	v_mfma_f32_32x32x16_bf16 v[66:81], v[226:229], v[154:157], v[50:65]
	ds_read2_b64 v[226:229], v3 offset0:64 offset1:66
	s_waitcnt lgkmcnt(5)
	v_mfma_f32_32x32x16_bf16 v[66:81], v[230:233], v[150:153], v[66:81]
	ds_read2_b64 v[230:233], v0 offset0:96 offset1:98
	s_nop 3
	v_exp_f32_e32 v214, v82
	v_exp_f32_e32 v215, v83
	v_exp_f32_e32 v216, v84
	s_waitcnt lgkmcnt(5)
	v_mfma_f32_32x32x16_bf16 v[66:81], v[234:237], v[146:149], v[66:81]
	ds_read2_b64 v[234:237], v3 offset0:68 offset1:70
	v_exp_f32_e32 v217, v85
	v_exp_f32_e32 v218, v86
	v_exp_f32_e32 v219, v87
	s_waitcnt lgkmcnt(5)
	v_mfma_f32_32x32x16_bf16 v[66:81], v[238:241], v[126:129], v[66:81]
	ds_read2_b64 v[238:241], v0 offset0:100 offset1:102
	v_exp_f32_e32 v220, v88
	v_exp_f32_e32 v221, v89
	v_max3_f32 v159, v82, v83, v84
	v_max3_f32 v250, v85, v86, v87
	s_waitcnt lgkmcnt(5)
	v_mfma_f32_32x32x16_bf16 v[66:81], v[242:245], v[122:125], v[66:81]
	ds_read2_b64 v[242:245], v3 offset0:72 offset1:74
	v_exp_f32_e32 v222, v90
	v_exp_f32_e32 v223, v91
	v_exp_f32_e32 v224, v92
	s_waitcnt lgkmcnt(5)
	v_mfma_f32_32x32x16_bf16 v[66:81], v[246:249], v[118:121], v[66:81]
	ds_read2_b64 v[246:249], v0 offset0:104 offset1:106
	s_setprio 0
	v_exp_f32_e32 v225, v93
	v_exp_f32_e32 v12, v94
	v_exp_f32_e32 v13, v95
	v_exp_f32_e32 v14, v96
	v_exp_f32_e32 v15, v97
	v_max3_f32 v159, v159, v88, v89
	v_max3_f32 v250, v250, v90, v91
	v_max3_f32 v159, v159, v92, v93
	v_max3_f32 v250, v250, v94, v95
	v_max3_f32 v159, v159, v96, v97
	s_nop 1
	v_max3_f32 v159, v159, v66, v67
	v_max3_f32 v250, v250, v68, v69
	v_max3_f32 v159, v159, v70, v71
	v_max3_f32 v250, v250, v72, v73
	v_max3_f32 v159, v159, v74, v75
	v_max3_f32 v250, v250, v76, v77
	v_max3_f32 v159, v159, v78, v79
	v_max3_f32 v250, v250, v80, v81
	v_max_f32_e32 v0, v159, v250
	v_mov_b32_e32 v3, v0
	s_nop 1
	v_permlane32_swap_b32_e32 v0, v3
	v_max_f32_e32 v0, v0, v3
	s_nop 0
	v_cmp_lt_f32_e32 vcc, s30, v0
	s_cbranch_vccnz .Lat_r1

; #define LAS __attribute__((address_space(3)))
; #define MFMA32(a, b, c) __builtin_amdgcn_mfma_f32_32x32x16_bf16((a), (b), (c), 0, 0, 0)
; DI int crow(int r, int hi) { return (r & 3) + 8 * (r >> 2) + 4 * hi; }
; DI float max2f(float a, float b) { float r; asm("v_max_f32_e32 %0, %1, %2" : "=v"(r) : "v"(a), "v"(b)); return r; }
; DI void attn_tile(bool MASK, const LAS unsigned char* Ks, const LAS unsigned char* Vs, const bf16x8 (&qr)[6], f32x16& negm, float& mrun, float& lrun, f32x16& o0, f32x16& o1,
;                                        int kv0, int qrow, int r32, int hi) {
;     ...
;     __builtin_amdgcn_s_setprio(1);
;     {
;         const bf16x8 a0 = *(const LAS bf16x8*)(Ks + r32 * 208 + hi * 16);
;         const bf16x8 a1 = *(const LAS bf16x8*)(Ks + (32 + r32) * 208 + hi * 16);
;         p0 = MFMA32(a0, qr[0], negm); p1 = MFMA32(a1, qr[0], negm);
;     }
; #pragma unroll
;     for (int d0 = 1; d0 < 6; ++d0) {
;         const bf16x8 a0 = *(const LAS bf16x8*)(Ks + r32 * 208 + (2 * d0 + hi) * 16);
;         const bf16x8 a1 = *(const LAS bf16x8*)(Ks + (32 + r32) * 208 + (2 * d0 + hi) * 16);
;         p0 = MFMA32(a0, qr[d0], p0); p1 = MFMA32(a1, qr[d0], p1);
;     }
;     __builtin_amdgcn_s_setprio(0);
;     if (MASK) {
;         asm volatile("" ::: "memory");
; #pragma unroll
;         for (int r = 0; r < 16; ++r) { const int kv = kv0 + crow(r, hi); if (kv > qrow) p0[r] = -INFINITY; if (kv + 32 > qrow) p1[r] = -INFINITY; }
;     }
;     float mxa = max3f(p0[0], p0[1], p1[0]), mxb = max3f(p0[2], p0[3], p1[1]); mxa = max3f(mxa, p1[2], p1[3]);
; #pragma unroll
;     for (int r = 4; r < 16; r += 4) { mxa = max3f(mxa, p0[r], p0[r + 1]); mxb = max3f(mxb, p0[r + 2], p0[r + 3]); mxa = max3f(mxa, p1[r], p1[r + 1]); mxb = max3f(mxb, p1[r + 2], p1[r + 3]); }
;     float mx = max2f(mxa, mxb);
;     mx = max2f(mx, __shfl_xor(mx, 32));
;     if (__any(mx > AT_THR)) {
;         const float dm = max2f(mx, 0.f);
;         const float alpha = __builtin_amdgcn_exp2f(-dm);
;         mrun += dm; lrun *= alpha;
; #pragma unroll
;         for (int r = 0; r < 16; ++r) { o0[r] *= alpha; o1[r] *= alpha; p0[r] -= dm; p1[r] -= dm; negm[r] = -mrun; }
;     }
; DI void attn_unit(int b, int h, int qb, const bf16* Qb, const bf16* Kb, const bf16* Vt, const int* positions, bf16* O, LAS unsigned char* lds, int tid) {
;     ...
;         AT_COMMIT(A, 0); AT_ISSUE(A, t + 6);
;         AT_TILE(t + 2, 2);
.LBB0_862:
	s_add_i32 s33, s23, 6
	s_min_i32 s33, s33, s20
	v_mad_i64_i32 v[4:5], s[34:35], s33, v161, v[190:191]
	v_mad_i64_i32 v[6:7], s[34:35], s33, v161, v[194:195]
	s_lshl_b32 s34, s33, 6
	s_waitcnt lgkmcnt(0)
	s_barrier
	s_waitcnt vmcnt(6)
	ds_write_b128 v209, v[142:145]
	ds_write_b128 v210, v[138:141]
	ds_write2_b64 v211, v[134:135], v[136:137] offset1:1
	s_ashr_i32 s35, s34, 31
	global_load_dwordx4 v[142:145], v[4:5], off
	global_load_dwordx4 v[138:141], v[6:7], off
	v_lshl_add_u64 v[4:5], s[34:35], 1, v[192:193]
	global_load_dwordx4 v[134:137], v[4:5], off
	s_add_i32 s33, s23, 2
	s_cmp_ge_i32 s33, s19
	s_cbranch_scc1 .LBB0_848
	s_add_i32 s34, s21, 0x80
	s_cmp_gt_i32 s34, s22
	s_cbranch_scc1 .LBB0_848
	s_cmp_lt_i32 s33, s12
	s_setprio 1
	v_add_u32_e32 v0, v206, v160
	ds_read_b128 v[4:7], v0 offset:44032
	ds_read_b128 v[8:11], v0 offset:44064
	ds_read_b128 v[12:15], v0 offset:44096
	ds_read_b128 v[214:217], v0 offset:44128
	ds_read_b128 v[218:221], v0 offset:44160
	ds_read_b128 v[222:225], v0 offset:44192
	ds_read_b128 v[226:229], v0 offset:50688
	ds_read_b128 v[230:233], v0 offset:50720
	s_waitcnt lgkmcnt(7)
	v_mfma_f32_32x32x16_bf16 v[82:97], v[4:7], v[154:157], v[50:65]
	ds_read_b128 v[234:237], v0 offset:50752
	s_waitcnt lgkmcnt(7)
	v_mfma_f32_32x32x16_bf16 v[82:97], v[8:11], v[150:153], v[82:97]
	ds_read_b128 v[238:241], v0 offset:50784
	s_waitcnt lgkmcnt(7)
	v_mfma_f32_32x32x16_bf16 v[82:97], v[12:15], v[146:149], v[82:97]
	ds_read_b128 v[242:245], v0 offset:50816
	s_waitcnt lgkmcnt(7)
	v_mfma_f32_32x32x16_bf16 v[82:97], v[214:217], v[126:129], v[82:97]
	ds_read_b128 v[246:249], v0 offset:50848
	s_waitcnt lgkmcnt(7)
	v_mfma_f32_32x32x16_bf16 v[82:97], v[218:221], v[122:125], v[82:97]
	s_waitcnt lgkmcnt(6)
	v_mfma_f32_32x32x16_bf16 v[82:97], v[222:225], v[118:121], v[82:97]
	s_cbranch_scc0 .Lat_m2
	s_setprio 0
	v_add_u32_e32 v3, v205, v208
	v_add_u32_e32 v0, 0xf000, v3
	v_add_u32_e32 v3, 0xe000, v3
	s_waitcnt lgkmcnt(5)
	v_mfma_f32_32x32x16_bf16 v[66:81], v[226:229], v[154:157], v[50:65]
	ds_read2_b64 v[226:229], v3 offset1:2
	s_waitcnt lgkmcnt(5)
	v_mfma_f32_32x32x16_bf16 v[66:81], v[230:233], v[150:153], v[66:81]
	ds_read2_b64 v[230:233], v0 offset0:32 offset1:34
	s_nop 3
	v_exp_f32_e32 v214, v82
	v_exp_f32_e32 v215, v83
	v_exp_f32_e32 v216, v84
	s_waitcnt lgkmcnt(5)
	v_mfma_f32_32x32x16_bf16 v[66:81], v[234:237], v[146:149], v[66:81]
	ds_read2_b64 v[234:237], v3 offset0:4 offset1:6
	v_exp_f32_e32 v217, v85
	v_exp_f32_e32 v218, v86
	v_exp_f32_e32 v219, v87
	s_waitcnt lgkmcnt(5)
	v_mfma_f32_32x32x16_bf16 v[66:81], v[238:241], v[126:129], v[66:81]
	ds_read2_b64 v[238:241], v0 offset0:36 offset1:38
	v_exp_f32_e32 v220, v88
	v_exp_f32_e32 v221, v89
	v_max3_f32 v159, v82, v83, v84
	v_max3_f32 v250, v85, v86, v87
	s_waitcnt lgkmcnt(5)
	v_mfma_f32_32x32x16_bf16 v[66:81], v[242:245], v[122:125], v[66:81]
	ds_read2_b64 v[242:245], v3 offset0:8 offset1:10
	v_exp_f32_e32 v222, v90
	v_exp_f32_e32 v223, v91
	v_exp_f32_e32 v224, v92
	s_waitcnt lgkmcnt(5)
	v_mfma_f32_32x32x16_bf16 v[66:81], v[246:249], v[118:121], v[66:81]
	ds_read2_b64 v[246:249], v0 offset0:40 offset1:42
	s_setprio 0
	v_exp_f32_e32 v225, v93
	v_exp_f32_e32 v12, v94
	v_exp_f32_e32 v13, v95
	v_exp_f32_e32 v14, v96
	v_exp_f32_e32 v15, v97
	v_max3_f32 v159, v159, v88, v89
	v_max3_f32 v250, v250, v90, v91
	v_max3_f32 v159, v159, v92, v93
	v_max3_f32 v250, v250, v94, v95
	v_max3_f32 v159, v159, v96, v97
	s_nop 1
	v_max3_f32 v159, v159, v66, v67
	v_max3_f32 v250, v250, v68, v69
	v_max3_f32 v159, v159, v70, v71
	v_max3_f32 v250, v250, v72, v73
	v_max3_f32 v159, v159, v74, v75
	v_max3_f32 v250, v250, v76, v77
	v_max3_f32 v159, v159, v78, v79
	v_max3_f32 v250, v250, v80, v81
	v_max_f32_e32 v0, v159, v250
	v_mov_b32_e32 v3, v0
	s_nop 1
	v_permlane32_swap_b32_e32 v0, v3
	v_max_f32_e32 v0, v0, v3
	s_nop 0
	v_cmp_lt_f32_e32 vcc, s30, v0
	s_cbranch_vccnz .Lat_r2
